# dense attention loop bodies (branch-target blocks) aligned to 64 bytes
# speedup vs baseline: 1.0139x; 1.0003x over previous
; #define RAW_BARRIER() do { asm volatile("s_waitcnt lgkmcnt(0)" ::: "memory"); __builtin_amdgcn_s_barrier(); } while (0)
; template <int DK, int QB, bool NA>
; DEVI void attn_item(const AttnArgs& a, unsigned char* smem) {
;     ...
;   for (int j = 0; j < nt; ++j) {
;     if (j + 1 < nt) {
;       if constexpr (DK == 96) asm volatile("s_waitcnt vmcnt(5)" ::: "memory");
;       else                    asm volatile("s_waitcnt vmcnt(4)" ::: "memory");
;     } else {
;       asm volatile("s_waitcnt vmcnt(0)" ::: "memory");
;     }
;     RAW_BARRIER();
;     if (j + 2 < nt) ATT_ISSUE(j + 2, is);
;     is = (is + 1 == S) ? 0 : is + 1;
;     const unsigned cur = lbase + cs * ATT_STAGE;
;     cs = (cs + 1 == S) ? 0 : cs + 1;
;     if (wact) {
.LBB0_2266:
	s_or_b64 exec, exec, s[42:43]
	s_mov_b32 s3, 1
	s_mov_b32 s9, 2
	s_movk_i32 s44, 0xc0
	s_waitcnt vmcnt(0)
	s_branch .LBB0_2269
	.p2align	6

; #define RAW_BARRIER() do { asm volatile("s_waitcnt lgkmcnt(0)" ::: "memory"); __builtin_amdgcn_s_barrier(); } while (0)
; template <int DK, int QB, bool NA>
; DEVI void attn_item(const AttnArgs& a, unsigned char* smem) {
;     ...
;   for (int j = 0; j < nt; ++j) {
;     if (j + 1 < nt) {
;       if constexpr (DK == 96) asm volatile("s_waitcnt vmcnt(5)" ::: "memory");
;       else                    asm volatile("s_waitcnt vmcnt(4)" ::: "memory");
;     } else {
;       asm volatile("s_waitcnt vmcnt(0)" ::: "memory");
;     }
;     RAW_BARRIER();
;     if (j + 2 < nt) ATT_ISSUE(j + 2, is);
;     is = (is + 1 == S) ? 0 : is + 1;
;     const unsigned cur = lbase + cs * ATT_STAGE;
;     cs = (cs + 1 == S) ? 0 : cs + 1;
;     if (wact) {
.LBB0_2311:
	s_or_b64 exec, exec, s[2:3]
	s_mov_b32 s8, 1
	s_mov_b32 s42, 2
	s_movk_i32 s43, 0xc0
	s_waitcnt vmcnt(0)
	s_branch .LBB0_2314
	.p2align	6
